# L1 attention: waves 4-7 staggered half a KV tile behind waves 0-3 (two barriers per tile, early tile store by the lagging half)
# speedup vs baseline: 1.0077x; 1.0077x over previous
; template <int DQK, int MODE>
; DI void attn_phase(const bf16_t* __restrict__ QK, int ldq, const bf16_t* __restrict__ Vt, int VC, bf16_t* __restrict__ O, int ldo, int nhu, bool skip_ctx, const float* __restrict__ qgain, const f32x2* __restrict__ rope, float qscale, char* shm) {
;     ...
;     const int tid = tx, w = tid >> 6, lane = tid & 63, r = lane & 31, h = lane >> 5;
;     const int nlat = NB * nhu * 8, nunits = nlat + (skip_ctx ? 0 : NB * nhu);
;     for (int u = bx; u < nunits; u += gridDim.x) {
;         int qt, hu, b;
;         if (u < nlat) { qt = 1 + (u & 7); hu = (u >> 3) % nhu; b = (u >> 3) / nhu; } else { const int v = u - nlat; qt = 0; hu = v % nhu; b = v / nhu; }
;         const int qoff = hu * DQK, koff = 1024 + (MODE == 0 ? hu * 64 : (hu >> 2) * 128), voff = (MODE == 0 ? (hu >> 1) : (hu >> 2)) * 128, ooff = hu * 128;
;         const int nkt = qt == 0 ? 4 : 36;
;         const size_t qrow = (size_t)b * LT + qt * 256 + w * 32 + r;
;         bf16x8 qf[DQK / 16];
; #pragma unroll
;         for (int ks = 0; ks < DQK / 16; ++ks) qf[ks] = *(const bf16x8*)(QK + qrow * ldq + qoff + ks * 16 + h * 8);
;         {
;             float ss = 0.f;
; #pragma unroll
;             for (int ks = 0; ks < DQK / 16; ++ks) { const u32x4 wq = __builtin_bit_cast(u32x4, qf[ks]);
;                 const float a0 = bflo(wq.x), a1 = bfhi(wq.x), a2 = bflo(wq.y), a3 = bfhi(wq.y), a4 = bflo(wq.z), a5 = bfhi(wq.z), a6 = bflo(wq.w), a7 = bfhi(wq.w);
;                 ss += a0 * a0 + a1 * a1 + a2 * a2 + a3 * a3 + a4 * a4 + a5 * a5 + a6 * a6 + a7 * a7; }
;             ss += __shfl_xor(ss, 32);
;             const float rr = rsqrtf(ss * (1.f / DQK) + EPS) * qscale; int go = (MODE == 0 ? (hu & 1) * 64 : 0) + h * 8; asm volatile("" : "+v"(go));
;             const float* gq = qgain + go; const f32x2* rp = rope + (size_t)((qt > 0 ? qt - 1 : 0) * 256 + w * 32 + r) * (DQK / 2) + h * 8;
; #pragma unroll
;             for (int ks = 0; ks < DQK / 32; ++ks) {
;                 const u32x4 wa = __builtin_bit_cast(u32x4, qf[ks]), wb = __builtin_bit_cast(u32x4, qf[ks + DQK / 32]);
;                 float xa[8] = {bflo(wa.x), bfhi(wa.x), bflo(wa.y), bfhi(wa.y), bflo(wa.z), bfhi(wa.z), bflo(wa.w), bfhi(wa.w)};
;                 float xb[8] = {bflo(wb.x), bfhi(wb.x), bflo(wb.y), bfhi(wb.y), bflo(wb.z), bfhi(wb.z), bflo(wb.w), bfhi(wb.w)};
; #pragma unroll
.LBB0_1283:
	s_or_b64 exec, exec, s[0:1]
	s_waitcnt lgkmcnt(0)
	v_mov_b32_e32 v0, v252
	s_mov_b32 s7, s87
	s_barrier
	v_readfirstlane_b32 s100, v252
	s_nop 3
	s_lshr_b32 s100, s100, 8
	s_sub_u32 s100, 0, s100
	s_mov_b32 s101, s100
	s_not_b64 s[98:99], s[100:101]
	s_cmpk_gt_i32 s7, 0x47f
	s_cbranch_scc1 .LBB0_1330
	v_ashrrev_i32_e32 v2, 1, v0
	v_and_b32_e32 v4, 31, v0
	v_and_b32_e32 v3, 0xffffffe0, v2
	v_ashrrev_i32_e32 v125, 31, v3
	v_or_b32_e32 v124, v3, v4
	v_mbcnt_hi_u32_b32 v3, -1, v253
	s_movk_i32 s0, 0xffe0
	v_and_b32_e32 v6, 64, v3
	v_xor_b32_e32 v5, 32, v3
	v_add_u32_e32 v6, 64, v6
	v_bfi_b32 v2, s0, v2, v0
	v_cmp_lt_i32_e32 vcc, v5, v6
	v_add_u32_e32 v157, 0xffffff00, v2
	v_ashrrev_i32_e32 v2, 31, v0
	v_cndmask_b32_e32 v3, v3, v5, vcc
	v_lshrrev_b32_e32 v2, 29, v2
	v_lshlrev_b32_e32 v127, 2, v3
	v_add_u32_e32 v3, v0, v2
	v_ashrrev_i32_e32 v2, 3, v3
	v_and_b32_e32 v3, -8, v3
	v_sub_u32_e32 v5, v0, v3
	v_ashrrev_i32_e32 v3, 31, v2
	s_movk_i32 s4, 0x90
	v_bfe_u32 v1, v0, 5, 1
	v_lshlrev_b64 v[132:133], 12, v[2:3]
	v_lshlrev_b32_e32 v134, 3, v5
	v_mul_lo_u32 v2, v2, s4
	v_lshlrev_b32_e32 v5, 4, v5
	v_mov_b32_e32 v129, 0
	v_lshlrev_b32_e32 v128, 6, v1
	v_lshlrev_b32_e32 v3, 3, v0
	v_add3_u32 v158, 0, v2, v5
	v_lshlrev_b32_e32 v2, 4, v0
	v_lshl_add_u64 v[130:131], s[10:11], 0, v[128:129]
	v_and_b32_e32 v5, 0x60, v2
	v_and_b32_e32 v3, 8, v3
	v_and_b32_e32 v128, 0x70, v2
	v_ashrrev_i32_e32 v2, 3, v0
	s_movk_i32 s5, 0x1200
	v_add_u32_e32 v0, 0x200, v0
	v_lshlrev_b32_e32 v126, 3, v1
	v_add3_u32 v159, 0, v5, v3
	v_mul_u32_u24_e32 v3, 0x90, v4
	v_lshlrev_b32_e32 v1, 4, v1
	v_mad_i64_i32 v[138:139], s[0:1], v2, s5, 0
	v_ashrrev_i32_e32 v0, 3, v0
	v_mad_i64_i32 v[140:141], s[0:1], v0, s5, 0
	v_mul_lo_u32 v161, v0, s4
	v_add3_u32 v162, 0, v3, v1
	v_add3_u32 v163, 0, v1, v3
	v_or_b32_e32 v0, v138, v128
	v_mov_b32_e32 v1, v139
	v_lshl_add_u64 v[0:1], s[68:69], 0, v[0:1]
	s_mov_b64 s[0:1], 0x92da080
	v_lshl_add_u64 v[142:143], v[0:1], 0, s[0:1]
	v_or_b32_e32 v0, v140, v128
	v_mov_b32_e32 v1, v141
	v_ashrrev_i32_e32 v135, 31, v134
	v_lshl_add_u64 v[0:1], s[68:69], 0, v[0:1]
	v_lshl_add_u64 v[144:145], v[0:1], 0, s[0:1]
	v_lshl_add_u64 v[0:1], v[134:135], 1, v[132:133]
	s_add_u32 s2, s68, 0xb6da000
	v_lshl_add_u64 v[0:1], s[68:69], 0, v[0:1]
	s_mov_b64 s[0:1], 0x4b1a800
	s_addc_u32 s3, s69, 0
	v_lshl_add_u64 v[136:137], s[8:9], 0, v[128:129]
	v_mul_lo_u32 v160, v2, s4
	v_lshl_add_u64 v[146:147], v[0:1], 0, s[0:1]
	v_mov_b32_e32 v164, 0x358637bd
	s_mov_b32 s30, 0x800000
	s_mov_b64 s[4:5], 0x80
	s_mov_b64 s[8:9], 0x40000
	v_lshlrev_b32_e32 v128, 1, v126
	v_mov_b32_e32 v165, 0x1200
	s_branch .LBB0_1288

; DI unsigned pack2(float lo, float hi) { const f32x2 v = (f32x2){lo, hi}; return __builtin_bit_cast(unsigned, __builtin_convertvector(v, bf16x2_t)); }
; DI float half_swap_sum(float x) { const unsigned u = __float_as_uint(x); const auto r = __builtin_amdgcn_permlane32_swap(u, u, false, false); return __uint_as_float(r[0]) + __uint_as_float(r[1]); }
; template <int DQK, int MODE>
; DI void attn_phase(const bf16_t* __restrict__ QK, int ldq, const bf16_t* __restrict__ Vt, int VC, bf16_t* __restrict__ O, int ldo, int nhu, bool skip_ctx, const float* __restrict__ qgain, const f32x2* __restrict__ rope, float qscale, char* shm) {
;     ...
;             { const f32x2 m2 = (f32x2){mrun, mrun}; f32x2 ps2 = (f32x2){0.f, 0.f};
; #pragma unroll
;               for (int i = 0; i < 16; i += 2) {
;                   f32x2 a = (f32x2){st0[i], st0[i + 1]} - m2, c = (f32x2){st1[i], st1[i + 1]} - m2;
;                   a[0] = __builtin_amdgcn_exp2f(a[0]); a[1] = __builtin_amdgcn_exp2f(a[1]); c[0] = __builtin_amdgcn_exp2f(c[0]); c[1] = __builtin_amdgcn_exp2f(c[1]);
;                   ps2 += a; ps2 += c; st0[i] = a[0]; st0[i + 1] = a[1]; st1[i] = c[0]; st1[i + 1] = c[1]; }
;               lsum += ps2[0] + ps2[1]; }
; #pragma unroll
;             for (int kb = 0; kb < 2; ++kb)
; #pragma unroll
;                 for (int s = 0; s < 2; ++s) {
;                     u32x4 pw;
;                     if (kb == 0) { pw.x = pack2(st0[8 * s], st0[8 * s + 1]); pw.y = pack2(st0[8 * s + 2], st0[8 * s + 3]); pw.z = pack2(st0[8 * s + 4], st0[8 * s + 5]); pw.w = pack2(st0[8 * s + 6], st0[8 * s + 7]); }
;                     else { pw.x = pack2(st1[8 * s], st1[8 * s + 1]); pw.y = pack2(st1[8 * s + 2], st1[8 * s + 3]); pw.z = pack2(st1[8 * s + 4], st1[8 * s + 5]); pw.w = pack2(st1[8 * s + 6], st1[8 * s + 7]); }
;                     const bf16x8 pb = __builtin_bit_cast(bf16x8, pw);
; #pragma unroll
;                     for (int t = 0; t < 4; ++t) {
;                         const bf16x8 a = *(const bf16x8*)(Vc + (32 * t + r) * VS + (kb * 2 + s) * 32 + h * 16);
;                         oacc[t] = MFMA32(a, pb, oacc[t]);
;                     }
;                 }
;             if (kt + 1 < nkt) ATT_STORE((kt + 1) & 1);
;             __syncthreads();
;         }
;     ...
;         const float l = half_swap_sum(lsum), inv = 1.f / l;
.LBB0_1287:
	s_waitcnt lgkmcnt(0)
	s_barrier
	v_mov_b32_e32 v97, v156
	v_pk_add_f32 v[80:81], v[80:81], v[96:97] neg_lo:[0,1] neg_hi:[0,1]
	v_pk_add_f32 v[88:89], v[88:89], v[96:97] neg_lo:[0,1] neg_hi:[0,1]
	v_exp_f32_e32 v114, v80
	v_exp_f32_e32 v115, v81
	v_pk_add_f32 v[80:81], v[82:83], v[96:97] neg_lo:[0,1] neg_hi:[0,1]
	ds_read_b128 v[98:101], v163 offset:36896
	v_exp_f32_e32 v116, v80
	v_exp_f32_e32 v117, v81
	v_pk_add_f32 v[80:81], v[84:85], v[96:97] neg_lo:[0,1] neg_hi:[0,1]
	v_pk_add_f32 v[84:85], v[86:87], v[96:97] neg_lo:[0,1] neg_hi:[0,1]
	v_exp_f32_e32 v118, v80
	v_exp_f32_e32 v119, v81
	ds_read_b128 v[80:83], v163 offset:36864
	v_exp_f32_e32 v120, v84
	v_exp_f32_e32 v121, v85
	v_cvt_pk_bf16_f32 v84, v114, v115
	v_cvt_pk_bf16_f32 v85, v116, v117
	v_cvt_pk_bf16_f32 v86, v118, v119
	v_cvt_pk_bf16_f32 v87, v120, v121
	v_exp_f32_e32 v122, v88
	v_exp_f32_e32 v123, v89
	s_waitcnt lgkmcnt(0)
	v_mfma_f32_32x32x16_bf16 v[48:63], v[80:83], v[84:87], v[48:63]
	ds_read_b128 v[80:83], v163 offset:41472
	ds_read_b128 v[102:105], v163 offset:41504
	v_add_f32_e64 v64, v64, -v96
	v_add_f32_e64 v65, v65, -v97
	v_add_f32_e64 v72, v72, -v96
	v_add_f32_e64 v73, v73, -v97
	v_exp_f32_e32 v88, v64
	v_exp_f32_e32 v89, v65
	v_pk_add_f32 v[64:65], v[66:67], v[96:97] neg_lo:[0,1] neg_hi:[0,1]
	v_exp_f32_e32 v72, v72
	s_waitcnt lgkmcnt(1)
	v_mfma_f32_32x32x16_bf16 v[32:47], v[80:83], v[84:87], v[32:47]
	ds_read_b128 v[80:83], v163 offset:46080
	ds_read_b128 v[106:109], v163 offset:50688
	ds_read_b128 v[110:113], v163 offset:46112
	v_exp_f32_e32 v73, v73
	s_lshl_b32 s0, s31, 7
	s_ashr_i32 s1, s0, 31
	s_add_i32 s7, s7, s26
	s_cmpk_gt_i32 s7, 0x47f
	s_waitcnt lgkmcnt(2)
	v_mfma_f32_32x32x16_bf16 v[16:31], v[80:83], v[84:87], v[16:31]
	v_add_f32_e64 v80, v90, -v96
	v_add_f32_e64 v81, v91, -v97
	v_add_f32_e64 v90, v114, 0
	v_add_f32_e64 v91, v115, 0
	v_exp_f32_e32 v150, v80
	v_exp_f32_e32 v151, v81
	v_pk_add_f32 v[80:81], v[92:93], v[96:97] neg_lo:[0,1] neg_hi:[0,1]
	v_exp_f32_e32 v92, v64
	v_exp_f32_e32 v152, v80
	s_waitcnt lgkmcnt(1)
	v_mfma_f32_32x32x16_bf16 v[0:15], v[106:109], v[84:87], v[0:15]
	v_add_f32_e64 v84, v94, -v96
	v_add_f32_e64 v85, v95, -v97
	v_exp_f32_e32 v153, v81
	v_exp_f32_e32 v106, v84
	v_exp_f32_e32 v107, v85
	v_exp_f32_e32 v93, v65
	v_pk_add_f32 v[64:65], v[68:69], v[96:97] neg_lo:[0,1] neg_hi:[0,1]
	ds_read_b128 v[80:83], v163 offset:50720
	v_cvt_pk_bf16_f32 v84, v122, v123
	v_cvt_pk_bf16_f32 v85, v150, v151
	v_cvt_pk_bf16_f32 v86, v152, v153
	v_cvt_pk_bf16_f32 v87, v106, v107
	v_exp_f32_e32 v94, v64
	v_exp_f32_e32 v95, v65
	ds_read_b128 v[64:67], v163 offset:36928
	v_mfma_f32_32x32x16_bf16 v[48:63], v[98:101], v[84:87], v[48:63]
	v_add_f32_e64 v68, v70, -v96
	v_add_f32_e64 v69, v71, -v97
	v_cvt_pk_bf16_f32 v70, v94, v95
	v_exp_f32_e32 v98, v68
	v_exp_f32_e32 v99, v69
	v_cvt_pk_bf16_f32 v68, v88, v89
	v_cvt_pk_bf16_f32 v69, v92, v93
	v_cvt_pk_bf16_f32 v71, v98, v99
	v_mfma_f32_32x32x16_bf16 v[32:47], v[102:105], v[84:87], v[32:47]
	s_waitcnt lgkmcnt(2)
	v_mfma_f32_32x32x16_bf16 v[16:31], v[110:113], v[84:87], v[16:31]
	s_waitcnt lgkmcnt(0)
	v_mfma_f32_32x32x16_bf16 v[48:63], v[64:67], v[68:71], v[48:63]
	v_add_f32_e64 v64, v88, v90
	v_add_f32_e64 v65, v89, v91
	v_add_f32_e64 v64, v116, v64
	v_add_f32_e64 v65, v117, v65
	v_add_f32_e64 v64, v92, v64
	v_add_f32_e64 v65, v93, v65
	v_pk_add_f32 v[64:65], v[118:119], v[64:65]
	v_mfma_f32_32x32x16_bf16 v[0:15], v[80:83], v[84:87], v[0:15]
	ds_read_b128 v[80:83], v163 offset:41536
	ds_read_b128 v[84:87], v163 offset:36960
	v_add_f32_e64 v92, v94, v64
	v_add_f32_e64 v93, v95, v65
	ds_read_b128 v[64:67], v163 offset:46144
	ds_read_b128 v[88:91], v163 offset:41568
	s_waitcnt lgkmcnt(3)
	v_mfma_f32_32x32x16_bf16 v[32:47], v[80:83], v[68:71], v[32:47]
	v_add_f32_e64 v80, v120, v92
	v_add_f32_e64 v81, v121, v93
	v_add_f32_e64 v98, v98, v80
	v_add_f32_e64 v99, v99, v81
	ds_read_b128 v[80:83], v163 offset:50752
	ds_read_b128 v[92:95], v163 offset:46176
	s_waitcnt lgkmcnt(3)
	v_mfma_f32_32x32x16_bf16 v[16:31], v[64:67], v[68:71], v[16:31]
	v_add_f32_e64 v64, v74, -v96
	v_add_f32_e64 v65, v75, -v97
	v_exp_f32_e32 v74, v64
	v_exp_f32_e32 v75, v65
	v_pk_add_f32 v[64:65], v[76:77], v[96:97] neg_lo:[0,1] neg_hi:[0,1]
	s_nop 0
	v_exp_f32_e32 v76, v64
	s_waitcnt lgkmcnt(1)
	v_mfma_f32_32x32x16_bf16 v[0:15], v[80:83], v[68:71], v[0:15]
	v_add_f32_e64 v68, v78, -v96
	v_add_f32_e64 v69, v79, -v97
	v_add_f32_e64 v80, v122, v98
	v_add_f32_e64 v81, v123, v99
	v_exp_f32_e32 v77, v65
	v_exp_f32_e32 v78, v68
	v_cvt_pk_bf16_f32 v68, v72, v73
	v_pk_add_f32 v[72:73], v[72:73], v[80:81]
	v_exp_f32_e32 v79, v69
	v_pk_add_f32 v[72:73], v[150:151], v[72:73]
	ds_read_b128 v[64:67], v163 offset:50784
	v_pk_add_f32 v[72:73], v[74:75], v[72:73]
	v_cvt_pk_bf16_f32 v69, v74, v75
	v_pk_add_f32 v[72:73], v[152:153], v[72:73]
	v_cvt_pk_bf16_f32 v70, v76, v77
	v_pk_add_f32 v[72:73], v[76:77], v[72:73]
	v_cvt_pk_bf16_f32 v71, v78, v79
	v_pk_add_f32 v[72:73], v[106:107], v[72:73]
	s_waitcnt lgkmcnt(0)
	v_pk_add_f32 v[72:73], v[78:79], v[72:73]
	v_mfma_f32_32x32x16_bf16 v[48:63], v[84:87], v[68:71], v[48:63]
	v_add_f32_e32 v72, v72, v73
	v_add_f32_e32 v72, v166, v72
	v_mov_b32_e32 v73, v72
	s_nop 1
	v_permlane32_swap_b32_e32 v72, v73
	v_add_f32_e32 v72, v72, v73
	v_div_scale_f32 v73, s[10:11], v72, v72, 1.0
	v_rcp_f32_e32 v74, v73
	v_mfma_f32_32x32x16_bf16 v[32:47], v[88:91], v[68:71], v[32:47]
	s_mov_b64 vcc, s[100:101]
	s_cbranch_vccnz .Lat1_noend
	s_barrier
; DI unsigned pack2(float lo, float hi) { const f32x2 v = (f32x2){lo, hi}; return __builtin_bit_cast(unsigned, __builtin_convertvector(v, bf16x2_t)); }
; DI float half_swap_sum(float x) { const unsigned u = __float_as_uint(x); const auto r = __builtin_amdgcn_permlane32_swap(u, u, false, false); return __uint_as_float(r[0]) + __uint_as_float(r[1]); }
; template <int DQK, int MODE>
; DI void attn_phase(const bf16_t* __restrict__ QK, int ldq, const bf16_t* __restrict__ Vt, int VC, bf16_t* __restrict__ O, int ldo, int nhu, bool skip_ctx, const float* __restrict__ qgain, const f32x2* __restrict__ rope, float qscale, char* shm) {
;     ...
;         const float l = half_swap_sum(lsum), inv = 1.f / l;
;         bf16_t* op = O + qrow * ldo + ooff;
; #pragma unroll
;         for (int t = 0; t < 4; ++t)
; #pragma unroll
;             for (int g = 0; g < 4; g += 2) {
;                 const unsigned ax = pack2(oacc[t][4 * g] * inv, oacc[t][4 * g + 1] * inv), ay = pack2(oacc[t][4 * g + 2] * inv, oacc[t][4 * g + 3] * inv);
;                 const unsigned bx_ = pack2(oacc[t][4 * g + 4] * inv, oacc[t][4 * g + 5] * inv), by_ = pack2(oacc[t][4 * g + 6] * inv, oacc[t][4 * g + 7] * inv);
;                 const auto sx = __builtin_amdgcn_permlane32_swap(ax, bx_, false, false); const auto sy = __builtin_amdgcn_permlane32_swap(ay, by_, false, false);
;                 *(u32x4*)(op + 32 * t + 8 * (g + h)) = (u32x4){sx[0], sy[0], sx[1], sy[1]}; }
.Lat1_noend:
	v_fma_f32 v75, -v73, v74, 1.0
	v_fmac_f32_e32 v74, v75, v74
	v_mfma_f32_32x32x16_bf16 v[16:31], v[92:95], v[68:71], v[16:31]
	v_mfma_f32_32x32x16_bf16 v[0:15], v[64:67], v[68:71], v[0:15]
	v_div_scale_f32 v64, vcc, 1.0, v72, 1.0
	v_mul_f32_e32 v65, v64, v74
	v_fma_f32 v66, -v73, v65, v64
	v_fmac_f32_e32 v65, v66, v74
	v_fma_f32 v64, -v73, v65, v64
	v_div_fmas_f32 v64, v64, v74, v65
	v_div_fixup_f32 v64, v64, v72, 1.0
	v_pk_mul_f32 v[48:49], v[48:49], v[64:65] op_sel_hi:[1,0]
	v_pk_mul_f32 v[50:51], v[50:51], v[64:65] op_sel_hi:[1,0]
	v_pk_mul_f32 v[32:33], v[32:33], v[64:65] op_sel_hi:[1,0]
	v_pk_mul_f32 v[34:35], v[34:35], v[64:65] op_sel_hi:[1,0]
	v_pk_mul_f32 v[16:17], v[16:17], v[64:65] op_sel_hi:[1,0]
	v_pk_mul_f32 v[18:19], v[18:19], v[64:65] op_sel_hi:[1,0]
	v_pk_mul_f32 v[0:1], v[0:1], v[64:65] op_sel_hi:[1,0]
	v_pk_mul_f32 v[2:3], v[2:3], v[64:65] op_sel_hi:[1,0]
	v_lshl_add_u64 v[66:67], s[2:3], 0, v[148:149]
	v_cvt_pk_bf16_f32 v48, v48, v49
	v_cvt_pk_bf16_f32 v49, v50, v51
	v_pk_mul_f32 v[50:51], v[52:53], v[64:65] op_sel_hi:[1,0]
	v_pk_mul_f32 v[52:53], v[54:55], v[64:65] op_sel_hi:[1,0]
	v_cvt_pk_bf16_f32 v32, v32, v33
	v_cvt_pk_bf16_f32 v33, v34, v35
	v_pk_mul_f32 v[34:35], v[36:37], v[64:65] op_sel_hi:[1,0]
	v_pk_mul_f32 v[36:37], v[38:39], v[64:65] op_sel_hi:[1,0]
	v_cvt_pk_bf16_f32 v16, v16, v17
	v_cvt_pk_bf16_f32 v17, v18, v19
	v_pk_mul_f32 v[18:19], v[20:21], v[64:65] op_sel_hi:[1,0]
	v_pk_mul_f32 v[20:21], v[22:23], v[64:65] op_sel_hi:[1,0]
	v_cvt_pk_bf16_f32 v0, v0, v1
	v_cvt_pk_bf16_f32 v1, v2, v3
	v_pk_mul_f32 v[2:3], v[4:5], v[64:65] op_sel_hi:[1,0]
	v_pk_mul_f32 v[4:5], v[6:7], v[64:65] op_sel_hi:[1,0]
	v_lshl_add_u64 v[66:67], s[0:1], 1, v[66:67]
	v_cvt_pk_bf16_f32 v50, v50, v51
	v_cvt_pk_bf16_f32 v51, v52, v53
	v_cvt_pk_bf16_f32 v34, v34, v35
	v_cvt_pk_bf16_f32 v35, v36, v37
	v_cvt_pk_bf16_f32 v18, v18, v19
	v_cvt_pk_bf16_f32 v19, v20, v21
	v_cvt_pk_bf16_f32 v2, v2, v3
	v_cvt_pk_bf16_f32 v3, v4, v5
	v_permlane32_swap_b32_e32 v48, v50
	v_permlane32_swap_b32_e32 v49, v51
	v_lshl_add_u64 v[52:53], v[66:67], 0, v[128:129]
	v_permlane32_swap_b32_e32 v32, v34
	v_permlane32_swap_b32_e32 v33, v35
	v_permlane32_swap_b32_e32 v16, v18
	v_permlane32_swap_b32_e32 v17, v19
	v_permlane32_swap_b32_e32 v0, v2
	v_permlane32_swap_b32_e32 v1, v3
	global_store_dwordx4 v[52:53], v[48:51], off
	global_store_dwordx4 v[52:53], v[32:35], off offset:64
	global_store_dwordx4 v[52:53], v[16:19], off offset:128
	v_pk_mul_f32 v[48:49], v[56:57], v[64:65] op_sel_hi:[1,0]
	v_pk_mul_f32 v[50:51], v[58:59], v[64:65] op_sel_hi:[1,0]
	v_pk_mul_f32 v[32:33], v[40:41], v[64:65] op_sel_hi:[1,0]
	v_pk_mul_f32 v[34:35], v[42:43], v[64:65] op_sel_hi:[1,0]
	v_pk_mul_f32 v[16:17], v[24:25], v[64:65] op_sel_hi:[1,0]
	v_pk_mul_f32 v[18:19], v[26:27], v[64:65] op_sel_hi:[1,0]
	global_store_dwordx4 v[52:53], v[0:3], off offset:192
	v_cvt_pk_bf16_f32 v48, v48, v49
	v_cvt_pk_bf16_f32 v49, v50, v51
	v_pk_mul_f32 v[0:1], v[8:9], v[64:65] op_sel_hi:[1,0]
	v_pk_mul_f32 v[2:3], v[10:11], v[64:65] op_sel_hi:[1,0]
	v_pk_mul_f32 v[50:51], v[60:61], v[64:65] op_sel_hi:[1,0]
	v_pk_mul_f32 v[54:55], v[62:63], v[64:65] op_sel_hi:[1,0]
	v_cvt_pk_bf16_f32 v32, v32, v33
	v_cvt_pk_bf16_f32 v33, v34, v35
	v_pk_mul_f32 v[34:35], v[44:45], v[64:65] op_sel_hi:[1,0]
	v_pk_mul_f32 v[36:37], v[46:47], v[64:65] op_sel_hi:[1,0]
	v_cvt_pk_bf16_f32 v16, v16, v17
	v_cvt_pk_bf16_f32 v17, v18, v19
	v_pk_mul_f32 v[18:19], v[28:29], v[64:65] op_sel_hi:[1,0]
	v_pk_mul_f32 v[20:21], v[30:31], v[64:65] op_sel_hi:[1,0]
	v_cvt_pk_bf16_f32 v0, v0, v1
	v_cvt_pk_bf16_f32 v1, v2, v3
	v_pk_mul_f32 v[2:3], v[12:13], v[64:65] op_sel_hi:[1,0]
	v_pk_mul_f32 v[4:5], v[14:15], v[64:65] op_sel_hi:[1,0]
	v_cvt_pk_bf16_f32 v50, v50, v51
	v_cvt_pk_bf16_f32 v51, v54, v55
	v_cvt_pk_bf16_f32 v34, v34, v35
	v_cvt_pk_bf16_f32 v35, v36, v37
	v_cvt_pk_bf16_f32 v18, v18, v19
	v_cvt_pk_bf16_f32 v19, v20, v21
	v_cvt_pk_bf16_f32 v2, v2, v3
	v_cvt_pk_bf16_f32 v3, v4, v5
	v_permlane32_swap_b32_e32 v48, v50
	v_permlane32_swap_b32_e32 v49, v51
	v_permlane32_swap_b32_e32 v32, v34
	v_permlane32_swap_b32_e32 v33, v35
	v_permlane32_swap_b32_e32 v16, v18
	v_permlane32_swap_b32_e32 v17, v19
	v_permlane32_swap_b32_e32 v0, v2
	v_permlane32_swap_b32_e32 v1, v3
	global_store_dwordx4 v[52:53], v[48:51], off offset:32
	global_store_dwordx4 v[52:53], v[32:35], off offset:96
	global_store_dwordx4 v[52:53], v[16:19], off offset:160
	global_store_dwordx4 v[52:53], v[0:3], off offset:224
	s_cbranch_scc1 .LBB0_1330

; DI unsigned pack2(float lo, float hi) { const f32x2 v = (f32x2){lo, hi}; return __builtin_bit_cast(unsigned, __builtin_convertvector(v, bf16x2_t)); }
; template <int DQK, int MODE>
; DI void attn_phase(const bf16_t* __restrict__ QK, int ldq, const bf16_t* __restrict__ Vt, int VC, bf16_t* __restrict__ O, int ldo, int nhu, bool skip_ctx, const float* __restrict__ qgain, const f32x2* __restrict__ rope, float qscale, char* shm) {
;     ...
;                 qf[ks] = __builtin_bit_cast(bf16x8, (u32x4){pack2(xa[0], xa[1]), pack2(xa[2], xa[3]), pack2(xa[4], xa[5]), pack2(xa[6], xa[7])});
;                 qf[ks + DQK / 32] = __builtin_bit_cast(bf16x8, (u32x4){pack2(xb[0], xb[1]), pack2(xb[2], xb[3]), pack2(xb[4], xb[5]), pack2(xb[6], xb[7])});
;             }
;         }
;         f32x16 oacc[4];
; #pragma unroll
;         for (int t = 0; t < 4; ++t)
; #pragma unroll
;             for (int i = 0; i < 16; ++i) oacc[t][i] = 0.f;
;         float mrun = -1e30f, lsum = 0.f;
;         const bf16_t* kbase = QK + (size_t)b * LT * ldq + koff; const bf16_t* vbase = Vt + ((size_t)b * VC + voff) * LT;
;         u32x4 kreg[NKC], vreg[2];
;     ...
;         ATT_LOAD(0);
;     ...
;         __syncthreads();
;         ATT_STORE(0);
;         __syncthreads();
.LBB0_1326:
	s_ashr_i32 s11, s10, 31
	s_and_b32 s15, s12, 0xffffff80
	s_mul_i32 s35, s10, 0x900000
	s_mul_hi_i32 s34, s10, 0x900000
	s_add_u32 s36, s96, s35
	s_addc_u32 s37, s97, s34
	s_lshl_b64 s[0:1], s[12:13], 1
	s_add_u32 s12, s36, s0
	s_addc_u32 s13, s37, s1
	s_lshl_b64 s[10:11], s[10:11], 10
	s_ashr_i32 s36, s15, 31
	s_add_u32 s15, s10, s15
	s_addc_u32 s36, s11, s36
	v_lshl_add_u64 v[4:5], s[12:13], 0, v[132:133]
	v_mad_u64_u32 v[14:15], s[10:11], s15, v165, v[136:137]
	s_mulk_i32 s36, 0x1200
	v_lshl_add_u64 v[4:5], v[134:135], 1, v[4:5]
	v_add_u32_e32 v15, s36, v15
	v_lshl_add_u64 v[18:19], v[14:15], 0, v[138:139]
	global_load_dwordx4 v[48:51], v[4:5], off offset:2048
	global_load_dwordx4 v[52:55], v[18:19], off
	v_lshl_add_u64 v[4:5], v[14:15], 0, v[140:141]
	global_load_dwordx4 v[56:59], v[4:5], off
	v_cvt_pk_bf16_f32 v105, v10, v16
	v_cvt_pk_bf16_f32 v97, v11, v17
	v_add_u32_e32 v16, v159, v160
	v_add_u32_e32 v17, v159, v161
	s_sub_i32 s11, 0, s14
	v_mov_b32_e32 v14, v129
	v_mov_b32_e32 v15, v129
	v_add_u32_e32 v60, 0x2000, v16
	v_add_u32_e32 v61, 0x2000, v17
	s_add_u32 s0, s35, s0
	v_cvt_pk_bf16_f32 v104, v2, v6
	v_cvt_pk_bf16_f32 v106, v22, v26
	v_cvt_pk_bf16_f32 v107, v30, v34
	v_cvt_pk_bf16_f32 v96, v3, v7
	v_cvt_pk_bf16_f32 v98, v23, v27
	v_cvt_pk_bf16_f32 v99, v31, v35
	v_cvt_pk_bf16_f32 v108, v36, v32
	v_cvt_pk_bf16_f32 v109, v28, v24
	v_cvt_pk_bf16_f32 v110, v20, v12
	v_cvt_pk_bf16_f32 v111, v8, v0
	v_cvt_pk_bf16_f32 v100, v37, v33
	v_cvt_pk_bf16_f32 v101, v29, v25
	v_cvt_pk_bf16_f32 v102, v21, v13
	v_cvt_pk_bf16_f32 v103, v9, v1
	v_mov_b32_e32 v0, v129
	v_mov_b32_e32 v1, v129
	v_mov_b32_e32 v2, v129
	v_mov_b32_e32 v3, v129
	v_mov_b32_e32 v4, v129
	v_mov_b32_e32 v5, v129
	v_mov_b32_e32 v6, v129
	v_mov_b32_e32 v7, v129
	v_mov_b32_e32 v8, v129
	v_mov_b32_e32 v9, v129
	v_mov_b32_e32 v10, v129
	v_mov_b32_e32 v11, v129
	v_mov_b32_e32 v12, v129
	v_mov_b32_e32 v13, v129
	v_mov_b64_e32 v[30:31], v[14:15]
	v_mov_b64_e32 v[46:47], v[14:15]
	v_mad_u64_u32 v[150:151], s[12:13], s15, v165, v[142:143]
	v_mad_u64_u32 v[152:153], s[12:13], s15, v165, v[144:145]
	s_addc_u32 s1, s34, s1
	s_barrier
	s_mov_b32 s10, 1
	v_mov_b32_e32 v166, 0
	v_mov_b32_e32 v156, 0xf149f2ca
	v_mov_b64_e32 v[28:29], v[12:13]
	v_mov_b64_e32 v[26:27], v[10:11]
	v_mov_b64_e32 v[24:25], v[8:9]
	v_mov_b64_e32 v[22:23], v[6:7]
	v_mov_b64_e32 v[20:21], v[4:5]
	v_mov_b64_e32 v[18:19], v[2:3]
	v_mov_b64_e32 v[16:17], v[0:1]
	v_mov_b64_e32 v[44:45], v[12:13]
	v_mov_b64_e32 v[42:43], v[10:11]
	v_mov_b64_e32 v[40:41], v[8:9]
	v_mov_b64_e32 v[38:39], v[6:7]
	v_mov_b64_e32 v[36:37], v[4:5]
	v_mov_b64_e32 v[34:35], v[2:3]
	v_mov_b64_e32 v[32:33], v[0:1]
	v_add_u32_e32 v151, s36, v151
	s_waitcnt vmcnt(2)
	ds_write_b128 v158, v[48:51]
	s_waitcnt vmcnt(1)
	ds_write2_b64 v60, v[52:53], v[54:55] offset0:128 offset1:130
	s_waitcnt vmcnt(0)
	ds_write2_b64 v61, v[56:57], v[58:59] offset0:128 offset1:130
	v_mov_b64_e32 v[62:63], v[14:15]
	v_add_u32_e32 v153, s36, v153
	v_lshl_add_u64 v[154:155], v[146:147], 0, s[0:1]
	v_mov_b64_e32 v[60:61], v[12:13]
	v_mov_b64_e32 v[58:59], v[10:11]
	v_mov_b64_e32 v[56:57], v[8:9]
	v_mov_b64_e32 v[54:55], v[6:7]
	v_mov_b64_e32 v[52:53], v[4:5]
	v_mov_b64_e32 v[50:51], v[2:3]
	v_mov_b64_e32 v[48:49], v[0:1]
	s_waitcnt lgkmcnt(0)
	s_barrier
	s_mov_b64 vcc, s[100:101]
	s_cbranch_vccz .Lat1_nox
	s_barrier
.Lat1_nox:
	s_branch .LBB0_1328
.LBB0_1327:
	s_mov_b64 vcc, s[100:101]
	s_cbranch_vccz .Lat1_mid
	s_xor_b32 vcc_lo, s1, 0x6c00
	s_waitcnt vmcnt(0)
	v_add_u32_e32 v248, vcc_lo, v158
	ds_write_b128 v248, v[120:123]
	v_add_u32_e32 v248, vcc_lo, v159
	v_add_u32_e32 v249, v248, v160
	v_add_u32_e32 v248, v248, v161
	v_add_u32_e32 v249, 0x2000, v249
	v_add_u32_e32 v248, 0x2000, v248
	ds_write2_b64 v249, v[116:117], v[118:119] offset0:128 offset1:130
	ds_write2_b64 v248, v[112:113], v[114:115] offset0:128 offset1:130
; DI unsigned pack2(float lo, float hi) { const f32x2 v = (f32x2){lo, hi}; return __builtin_bit_cast(unsigned, __builtin_convertvector(v, bf16x2_t)); }
; #define MFMA32(a, b, c) __builtin_amdgcn_mfma_f32_32x32x16_bf16((a), (b), (c), 0, 0, 0)
; template <int DQK, int MODE>
; DI void attn_phase(const bf16_t* __restrict__ QK, int ldq, const bf16_t* __restrict__ Vt, int VC, bf16_t* __restrict__ O, int ldo, int nhu, bool skip_ctx, const float* __restrict__ qgain, const f32x2* __restrict__ rope, float qscale, char* shm) {
;     ...
;             { const f32x2 m2 = (f32x2){mrun, mrun}; f32x2 ps2 = (f32x2){0.f, 0.f};
; #pragma unroll
;               for (int i = 0; i < 16; i += 2) {
;                   f32x2 a = (f32x2){st0[i], st0[i + 1]} - m2, c = (f32x2){st1[i], st1[i + 1]} - m2;
;                   a[0] = __builtin_amdgcn_exp2f(a[0]); a[1] = __builtin_amdgcn_exp2f(a[1]); c[0] = __builtin_amdgcn_exp2f(c[0]); c[1] = __builtin_amdgcn_exp2f(c[1]);
;                   ps2 += a; ps2 += c; st0[i] = a[0]; st0[i + 1] = a[1]; st1[i] = c[0]; st1[i + 1] = c[1]; }
;               lsum += ps2[0] + ps2[1]; }
; #pragma unroll
;             for (int kb = 0; kb < 2; ++kb)
; #pragma unroll
;                 for (int s = 0; s < 2; ++s) {
;                     u32x4 pw;
;                     if (kb == 0) { pw.x = pack2(st0[8 * s], st0[8 * s + 1]); pw.y = pack2(st0[8 * s + 2], st0[8 * s + 3]); pw.z = pack2(st0[8 * s + 4], st0[8 * s + 5]); pw.w = pack2(st0[8 * s + 6], st0[8 * s + 7]); }
;                     else { pw.x = pack2(st1[8 * s], st1[8 * s + 1]); pw.y = pack2(st1[8 * s + 2], st1[8 * s + 3]); pw.z = pack2(st1[8 * s + 4], st1[8 * s + 5]); pw.w = pack2(st1[8 * s + 6], st1[8 * s + 7]); }
;                     const bf16x8 pb = __builtin_bit_cast(bf16x8, pw);
; #pragma unroll
;                     for (int t = 0; t < 4; ++t) {
;                         const bf16x8 a = *(const bf16x8*)(Vc + (32 * t + r) * VS + (kb * 2 + s) * 32 + h * 16);
;                         oacc[t] = MFMA32(a, pb, oacc[t]);
;                     }
;                 }
;             if (kt + 1 < nkt) ATT_STORE((kt + 1) & 1);
;             __syncthreads();
.Lat1_mid:
	s_waitcnt lgkmcnt(0)
	s_barrier
	v_pk_add_f32 v[80:81], v[80:81], v[156:157] op_sel_hi:[1,0] neg_lo:[0,1] neg_hi:[0,1]
	v_add_u32_e32 v167, s1, v163
	v_exp_f32_e32 v184, v80
	v_exp_f32_e32 v185, v81
	v_pk_add_f32 v[80:81], v[82:83], v[156:157] op_sel_hi:[1,0] neg_lo:[0,1] neg_hi:[0,1]
	ds_read_b128 v[168:171], v167 offset:9248
	v_exp_f32_e32 v186, v80
	v_exp_f32_e32 v187, v81
	v_pk_add_f32 v[80:81], v[84:85], v[156:157] op_sel_hi:[1,0] neg_lo:[0,1] neg_hi:[0,1]
	v_pk_add_f32 v[84:85], v[86:87], v[156:157] op_sel_hi:[1,0] neg_lo:[0,1] neg_hi:[0,1]
	v_exp_f32_e32 v188, v80
	v_exp_f32_e32 v189, v81
	ds_read_b128 v[80:83], v167 offset:9216
	v_exp_f32_e32 v190, v84
	v_exp_f32_e32 v191, v85
	v_cvt_pk_bf16_f32 v84, v184, v185
	v_cvt_pk_bf16_f32 v85, v186, v187
	v_cvt_pk_bf16_f32 v86, v188, v189
	v_cvt_pk_bf16_f32 v87, v190, v191
	v_pk_add_f32 v[88:89], v[88:89], v[156:157] op_sel_hi:[1,0] neg_lo:[0,1] neg_hi:[0,1]
	v_pk_add_f32 v[64:65], v[64:65], v[156:157] op_sel_hi:[1,0] neg_lo:[0,1] neg_hi:[0,1]
	s_waitcnt lgkmcnt(0)
	v_mfma_f32_32x32x16_bf16 v[48:63], v[80:83], v[84:87], v[48:63]
	ds_read_b128 v[80:83], v167 offset:13824
	ds_read_b128 v[172:175], v167 offset:13856
	v_exp_f32_e32 v192, v88
	v_exp_f32_e32 v193, v89
	v_exp_f32_e32 v88, v64
	v_exp_f32_e32 v89, v65
	v_pk_add_f32 v[64:65], v[184:185], 0 op_sel_hi:[1,0]
	v_pk_add_f32 v[72:73], v[72:73], v[156:157] op_sel_hi:[1,0] neg_lo:[0,1] neg_hi:[0,1]
	s_waitcnt lgkmcnt(1)
	v_mfma_f32_32x32x16_bf16 v[32:47], v[80:83], v[84:87], v[32:47]
	ds_read_b128 v[80:83], v167 offset:18432
	ds_read_b128 v[176:179], v167 offset:23040
	ds_read_b128 v[180:183], v167 offset:18464
	v_exp_f32_e32 v72, v72
	v_exp_f32_e32 v73, v73
	s_cmp_eq_u32 s0, 1
	s_cselect_b32 s0, 0x6c00, 0
	s_add_i32 s10, s10, 1
	s_waitcnt lgkmcnt(2)
	v_mfma_f32_32x32x16_bf16 v[16:31], v[80:83], v[84:87], v[16:31]
	v_add_f32_e64 v80, v90, -v156
	v_add_f32_e64 v81, v91, -v156
	v_add_f32_e64 v90, v88, v64
	v_add_f32_e64 v91, v89, v65
	v_exp_f32_e32 v194, v80
	v_exp_f32_e32 v195, v81
	v_pk_add_f32 v[80:81], v[92:93], v[156:157] op_sel_hi:[1,0] neg_lo:[0,1] neg_hi:[0,1]
	v_pk_add_f32 v[64:65], v[66:67], v[156:157] op_sel_hi:[1,0] neg_lo:[0,1] neg_hi:[0,1]
	v_exp_f32_e32 v196, v80
	s_waitcnt lgkmcnt(1)
	v_mfma_f32_32x32x16_bf16 v[0:15], v[176:179], v[84:87], v[0:15]
	v_add_f32_e64 v84, v94, -v156
	v_add_f32_e64 v85, v95, -v156
	v_exp_f32_e32 v197, v81
	v_exp_f32_e32 v176, v84
	v_exp_f32_e32 v177, v85
	v_exp_f32_e32 v92, v64
	v_exp_f32_e32 v93, v65
	v_pk_add_f32 v[64:65], v[68:69], v[156:157] op_sel_hi:[1,0] neg_lo:[0,1] neg_hi:[0,1]
	ds_read_b128 v[80:83], v167 offset:23072
	v_cvt_pk_bf16_f32 v84, v192, v193
	v_cvt_pk_bf16_f32 v85, v194, v195
	v_cvt_pk_bf16_f32 v86, v196, v197
	v_cvt_pk_bf16_f32 v87, v176, v177
	v_exp_f32_e32 v94, v64
	v_exp_f32_e32 v95, v65
	ds_read_b128 v[64:67], v167 offset:9280
	v_mfma_f32_32x32x16_bf16 v[48:63], v[168:171], v[84:87], v[48:63]
	v_add_f32_e64 v68, v70, -v156
	v_add_f32_e64 v69, v71, -v156
	v_cvt_pk_bf16_f32 v70, v94, v95
	v_exp_f32_e32 v168, v68
	v_exp_f32_e32 v169, v69
	v_cvt_pk_bf16_f32 v68, v88, v89
	v_cvt_pk_bf16_f32 v69, v92, v93
	v_lshl_add_u64 v[150:151], v[150:151], 0, s[4:5]
	v_mfma_f32_32x32x16_bf16 v[32:47], v[172:175], v[84:87], v[32:47]
	v_cvt_pk_bf16_f32 v71, v168, v169
	v_lshl_add_u64 v[152:153], v[152:153], 0, s[4:5]
	v_lshl_add_u64 v[154:155], v[154:155], 0, s[8:9]
	s_waitcnt lgkmcnt(2)
	v_mfma_f32_32x32x16_bf16 v[16:31], v[180:183], v[84:87], v[16:31]
	s_waitcnt lgkmcnt(0)
	v_mfma_f32_32x32x16_bf16 v[48:63], v[64:67], v[68:71], v[48:63]
	v_add_f32_e64 v64, v186, v90
	v_add_f32_e64 v65, v187, v91
	v_add_f32_e64 v64, v92, v64
	v_add_f32_e64 v65, v93, v65
	v_add_f32_e64 v64, v188, v64
	v_add_f32_e64 v65, v189, v65
	v_pk_add_f32 v[64:65], v[94:95], v[64:65]
	v_mfma_f32_32x32x16_bf16 v[0:15], v[80:83], v[84:87], v[0:15]
	ds_read_b128 v[80:83], v167 offset:13888
	ds_read_b128 v[84:87], v167 offset:9312
	v_add_f32_e64 v92, v190, v64
	v_add_f32_e64 v93, v191, v65
	ds_read_b128 v[64:67], v167 offset:18496
	ds_read_b128 v[88:91], v167 offset:13920
	s_waitcnt lgkmcnt(3)
	v_mfma_f32_32x32x16_bf16 v[32:47], v[80:83], v[68:71], v[32:47]
	v_add_f32_e64 v80, v168, v92
	v_add_f32_e64 v81, v169, v93
	v_add_f32_e64 v168, v192, v80
	v_add_f32_e64 v169, v193, v81
	ds_read_b128 v[80:83], v167 offset:23104
	ds_read_b128 v[92:95], v167 offset:18528
	s_waitcnt lgkmcnt(3)
	v_mfma_f32_32x32x16_bf16 v[16:31], v[64:67], v[68:71], v[16:31]
	v_add_f32_e64 v64, v74, -v156
	v_add_f32_e64 v65, v75, -v156
	v_exp_f32_e32 v74, v64
	v_exp_f32_e32 v75, v65
	v_pk_add_f32 v[64:65], v[76:77], v[156:157] op_sel_hi:[1,0] neg_lo:[0,1] neg_hi:[0,1]
	s_nop 0
	v_exp_f32_e32 v76, v64
	v_exp_f32_e32 v77, v65
	ds_read_b128 v[64:67], v167 offset:23136
	s_waitcnt lgkmcnt(2)
	v_mfma_f32_32x32x16_bf16 v[0:15], v[80:83], v[68:71], v[0:15]
	v_add_f32_e64 v68, v78, -v156
	v_add_f32_e64 v69, v79, -v156
	v_cvt_pk_bf16_f32 v70, v76, v77
	v_exp_f32_e32 v78, v68
	v_exp_f32_e32 v79, v69
	v_cvt_pk_bf16_f32 v68, v72, v73
	v_pk_add_f32 v[72:73], v[72:73], v[168:169]
	v_cvt_pk_bf16_f32 v69, v74, v75
	v_pk_add_f32 v[72:73], v[194:195], v[72:73]
	v_cvt_pk_bf16_f32 v71, v78, v79
	v_pk_add_f32 v[72:73], v[74:75], v[72:73]
	s_nop 0
	v_pk_add_f32 v[72:73], v[196:197], v[72:73]
	v_mfma_f32_32x32x16_bf16 v[48:63], v[84:87], v[68:71], v[48:63]
	v_add_f32_e64 v72, v76, v72
	v_add_f32_e64 v73, v77, v73
	v_add_f32_e64 v72, v176, v72
	v_add_f32_e64 v73, v177, v73
	v_add_f32_e64 v72, v78, v72
	v_add_f32_e64 v73, v79, v73
	v_add_f32_e32 v72, v72, v73
	v_mfma_f32_32x32x16_bf16 v[32:47], v[88:91], v[68:71], v[32:47]
	v_add_f32_e32 v166, v166, v72
	v_add_u32_e32 v72, s0, v158
	s_waitcnt vmcnt(2)
	ds_write_b128 v72, v[120:123]
	v_add_u32_e32 v72, s0, v159
	v_add_u32_e32 v73, v72, v160
	v_add_u32_e32 v72, v72, v161
	s_add_i32 s0, s11, s10
	s_waitcnt lgkmcnt(2)
	v_mfma_f32_32x32x16_bf16 v[16:31], v[92:95], v[68:71], v[16:31]
	v_add_u32_e32 v73, 0x2000, v73
	v_add_u32_e32 v72, 0x2000, v72
	s_cmp_eq_u32 s0, 2
	s_waitcnt vmcnt(1)
	ds_write2_b64 v73, v[116:117], v[118:119] offset0:128 offset1:130
	s_waitcnt vmcnt(0)
	ds_write2_b64 v72, v[112:113], v[114:115] offset0:128 offset1:130
	s_waitcnt lgkmcnt(0)
	s_barrier
	v_mfma_f32_32x32x16_bf16 v[0:15], v[64:67], v[68:71], v[0:15]
	s_cbranch_scc1 .LBB0_1285
